# combo18: combo11 with the 12 GEMM K-loop heads aligned to 64 bytes
# speedup vs baseline: 1.0018x; 1.0018x over previous
; template <class Epi, class Sched, bool ALIGN_EPI = false, bool SP2 = false>
; __device__ __forceinline__ void gemm_phase(PG8_LAS unsigned char* lds, const Gemm g, const Sched& S, const Epi& E, const int tid_arg) {
;     ...
;     for (;;) {
;         const bool has_next = S.next(ui + 1, nxt);
;         const char* nA = has_next ? (const char*)g.A + (size_t)nxt.pm * tstep : cA; const char* nB = has_next ? (const char*)g.Bt + (size_t)nxt.pn * tstep : cB;
;         for (int t = 0; t < nt; t += 2) {
;             const bool last = (t == nt - 2);
;             const char* a1 = cA + (size_t)(t + 1) * kstep;
;             const char* a2 = last ? nA : cA + (size_t)(t + 2) * kstep; const char* b2 = last ? nB : cB + (size_t)(t + 2) * kstep;
;             const char* a3 = a2 + kstep; const char* b3 = b2 + kstep;
;     ...
; #pragma unroll
;         for (int a = 0; a < 2; ++a)
; #pragma unroll
;             for (int b = 0; b < 2; ++b)
; #pragma unroll
;                 for (int m = 0; m < 4; ++m)
; #pragma unroll
;                     for (int n = 0; n < 2; ++n) acc[a][b][m][n] = (f32x4){0.f, 0.f, 0.f, 0.f};
.LBB0_252:
	s_ashr_i32 s23, s22, 31
	s_lshl_b64 s[0:1], s[22:23], 19
	s_add_u32 s24, s2, s0
	s_addc_u32 s25, s3, s1
	s_and_b64 s[0:1], s[4:5], exec
	s_cselect_b32 s23, s25, s35
	s_cselect_b32 s36, s24, s34
	s_ashr_i32 s21, s20, 31
	s_lshl_b64 s[0:1], s[20:21], 19
	s_add_u32 s26, s33, s0
	s_addc_u32 s27, s38, s1
	s_and_b64 s[0:1], s[4:5], exec
	s_cselect_b32 s21, s27, s9
	s_cselect_b32 s37, s26, s8
	s_add_u32 s68, s8, 0x100
	s_addc_u32 s69, s9, 0
	s_add_u32 s8, s34, 0x40080
	v_mov_b32_e32 v0, 0
	s_addc_u32 s9, s35, 0
	s_mov_b32 s70, -2
	v_mov_b32_e32 v1, v0
	v_mov_b64_e32 v[2:3], 0
	v_mov_b64_e32 v[4:5], 0
	v_mov_b64_e32 v[6:7], 0
	v_mov_b64_e32 v[16:17], 0
	v_mov_b64_e32 v[18:19], 0
	v_mov_b64_e32 v[20:21], 0
	v_mov_b64_e32 v[22:23], 0
	v_mov_b64_e32 v[32:33], 0
	v_mov_b64_e32 v[34:35], 0
	v_mov_b64_e32 v[36:37], 0
	v_mov_b64_e32 v[38:39], 0
	v_mov_b64_e32 v[48:49], 0
	v_mov_b64_e32 v[50:51], 0
	v_mov_b64_e32 v[52:53], 0
	v_mov_b64_e32 v[54:55], 0
	v_mov_b64_e32 v[8:9], 0
	v_mov_b64_e32 v[10:11], 0
	v_mov_b64_e32 v[12:13], 0
	v_mov_b64_e32 v[14:15], 0
	v_mov_b64_e32 v[24:25], 0
	v_mov_b64_e32 v[26:27], 0
	v_mov_b64_e32 v[28:29], 0
	v_mov_b64_e32 v[30:31], 0
	v_mov_b64_e32 v[40:41], 0
	v_mov_b64_e32 v[42:43], 0
	v_mov_b64_e32 v[44:45], 0
	v_mov_b64_e32 v[46:47], 0
	v_mov_b64_e32 v[56:57], 0
	v_mov_b64_e32 v[58:59], 0
	v_mov_b64_e32 v[60:61], 0
	v_mov_b64_e32 v[62:63], 0
	v_mov_b64_e32 v[64:65], 0
	v_mov_b64_e32 v[66:67], 0
	v_mov_b64_e32 v[68:69], 0
	v_mov_b64_e32 v[70:71], 0
	v_mov_b64_e32 v[80:81], 0
	v_mov_b64_e32 v[82:83], 0
	v_mov_b64_e32 v[84:85], 0
	v_mov_b64_e32 v[86:87], 0
	v_mov_b64_e32 v[96:97], 0
	v_mov_b64_e32 v[98:99], 0
	v_mov_b64_e32 v[100:101], 0
	v_mov_b64_e32 v[102:103], 0
	v_mov_b64_e32 v[112:113], 0
	v_mov_b64_e32 v[114:115], 0
	v_mov_b64_e32 v[116:117], 0
	v_mov_b64_e32 v[118:119], 0
	v_mov_b64_e32 v[72:73], 0
	v_mov_b64_e32 v[74:75], 0
	v_mov_b64_e32 v[76:77], 0
	v_mov_b64_e32 v[78:79], 0
	v_mov_b64_e32 v[88:89], 0
	v_mov_b64_e32 v[90:91], 0
	v_mov_b64_e32 v[92:93], 0
	v_mov_b64_e32 v[94:95], 0
	v_mov_b64_e32 v[104:105], 0
	v_mov_b64_e32 v[106:107], 0
	v_mov_b64_e32 v[108:109], 0
	v_mov_b64_e32 v[110:111], 0
	v_mov_b64_e32 v[120:121], 0
	v_mov_b64_e32 v[122:123], 0
	v_mov_b64_e32 v[124:125], 0
	v_mov_b64_e32 v[126:127], 0
	.p2alignl 6, 3212836864

; template <class Epi, class Sched, bool ALIGN_EPI = false, bool SP2 = false>
; __device__ __forceinline__ void gemm_phase(PG8_LAS unsigned char* lds, const Gemm g, const Sched& S, const Epi& E, const int tid_arg) {
;     ...
;     for (;;) {
;         const bool has_next = S.next(ui + 1, nxt);
;         const char* nA = has_next ? (const char*)g.A + (size_t)nxt.pm * tstep : cA; const char* nB = has_next ? (const char*)g.Bt + (size_t)nxt.pn * tstep : cB;
;         for (int t = 0; t < nt; t += 2) {
;             const bool last = (t == nt - 2);
;             const char* a1 = cA + (size_t)(t + 1) * kstep;
;             const char* a2 = last ? nA : cA + (size_t)(t + 2) * kstep; const char* b2 = last ? nB : cB + (size_t)(t + 2) * kstep;
;             const char* a3 = a2 + kstep; const char* b3 = b2 + kstep;
;     ...
; #pragma unroll
;         for (int a = 0; a < 2; ++a)
; #pragma unroll
;             for (int b = 0; b < 2; ++b)
; #pragma unroll
;                 for (int m = 0; m < 4; ++m)
; #pragma unroll
;                     for (int n = 0; n < 2; ++n) acc[a][b][m][n] = (f32x4){0.f, 0.f, 0.f, 0.f};
.LBB0_532:
	s_ashr_i32 s29, s28, 31
	s_lshl_b64 s[0:1], s[28:29], 19
	s_add_u32 s30, s2, s0
	s_addc_u32 s31, s3, s1
	s_and_b64 s[0:1], s[8:9], exec
	s_cselect_b32 s11, s31, s37
	s_cselect_b32 s29, s30, s36
	s_ashr_i32 s27, s26, 31
	s_lshl_b64 s[0:1], s[26:27], 19
	s_add_u32 s34, s33, s0
	s_addc_u32 s35, s38, s1
	s_and_b64 s[0:1], s[8:9], exec
	s_cselect_b32 s27, s35, s13
	s_cselect_b32 s62, s34, s12
	s_add_u32 s63, s12, 0x100
	s_addc_u32 s64, s13, 0
	s_add_u32 s12, s36, 0x40080
	v_mov_b32_e32 v0, 0
	s_addc_u32 s13, s37, 0
	s_mov_b32 s65, -2
	v_mov_b32_e32 v1, v0
	v_mov_b32_e32 v2, v0
	v_mov_b32_e32 v3, v0
	v_mov_b32_e32 v4, v0
	v_mov_b32_e32 v5, v0
	v_mov_b32_e32 v6, v0
	v_mov_b32_e32 v7, v0
	v_mov_b32_e32 v16, v0
	v_mov_b32_e32 v17, v0
	v_mov_b32_e32 v18, v0
	v_mov_b32_e32 v19, v0
	v_mov_b32_e32 v20, v0
	v_mov_b32_e32 v21, v0
	v_mov_b32_e32 v22, v0
	v_mov_b32_e32 v23, v0
	v_mov_b32_e32 v32, v0
	v_mov_b32_e32 v33, v0
	v_mov_b32_e32 v34, v0
	v_mov_b32_e32 v35, v0
	v_mov_b32_e32 v36, v0
	v_mov_b32_e32 v37, v0
	v_mov_b32_e32 v38, v0
	v_mov_b32_e32 v39, v0
	v_mov_b32_e32 v48, v0
	v_mov_b32_e32 v49, v0
	v_mov_b32_e32 v50, v0
	v_mov_b32_e32 v51, v0
	v_mov_b32_e32 v52, v0
	v_mov_b32_e32 v53, v0
	v_mov_b32_e32 v54, v0
	v_mov_b32_e32 v55, v0
	v_mov_b32_e32 v8, v0
	v_mov_b32_e32 v9, v0
	v_mov_b32_e32 v10, v0
	v_mov_b32_e32 v11, v0
	v_mov_b32_e32 v12, v0
	v_mov_b32_e32 v13, v0
	v_mov_b32_e32 v14, v0
	v_mov_b32_e32 v15, v0
	v_mov_b32_e32 v24, v0
	v_mov_b32_e32 v25, v0
	v_mov_b32_e32 v26, v0
	v_mov_b32_e32 v27, v0
	v_mov_b32_e32 v28, v0
	v_mov_b32_e32 v29, v0
	v_mov_b32_e32 v30, v0
	v_mov_b32_e32 v31, v0
	v_mov_b32_e32 v40, v0
	v_mov_b32_e32 v41, v0
	v_mov_b32_e32 v42, v0
	v_mov_b32_e32 v43, v0
	v_mov_b32_e32 v44, v0
	v_mov_b32_e32 v45, v0
	v_mov_b32_e32 v46, v0
	v_mov_b32_e32 v47, v0
	v_mov_b32_e32 v56, v0
	v_mov_b32_e32 v57, v0
	v_mov_b32_e32 v58, v0
	v_mov_b32_e32 v59, v0
	v_mov_b32_e32 v60, v0
	v_mov_b32_e32 v61, v0
	v_mov_b32_e32 v62, v0
	v_mov_b32_e32 v63, v0
	v_mov_b32_e32 v64, v0
	v_mov_b32_e32 v65, v0
	v_mov_b32_e32 v66, v0
	v_mov_b32_e32 v67, v0
	v_mov_b32_e32 v68, v0
	v_mov_b32_e32 v69, v0
	v_mov_b32_e32 v70, v0
	v_mov_b32_e32 v71, v0
	s_waitcnt vmcnt(0)
	v_mov_b32_e32 v80, v0
	v_mov_b32_e32 v81, v0
	v_mov_b32_e32 v82, v0
	v_mov_b32_e32 v83, v0
	v_mov_b32_e32 v84, v0
	v_mov_b32_e32 v85, v0
	v_mov_b32_e32 v86, v0
	v_mov_b32_e32 v87, v0
	v_mov_b32_e32 v96, v0
	v_mov_b32_e32 v97, v0
	v_mov_b32_e32 v98, v0
	v_mov_b32_e32 v99, v0
	v_mov_b32_e32 v100, v0
	v_mov_b32_e32 v101, v0
	v_mov_b32_e32 v102, v0
	v_mov_b32_e32 v103, v0
	v_mov_b32_e32 v112, v0
	v_mov_b32_e32 v113, v0
	v_mov_b32_e32 v114, v0
	v_mov_b32_e32 v115, v0
	v_mov_b32_e32 v116, v0
	v_mov_b32_e32 v117, v0
	v_mov_b32_e32 v118, v0
	v_mov_b32_e32 v119, v0
	v_mov_b32_e32 v72, v0
	v_mov_b32_e32 v73, v0
	v_mov_b32_e32 v74, v0
	v_mov_b32_e32 v75, v0
	v_mov_b32_e32 v76, v0
	v_mov_b32_e32 v77, v0
	v_mov_b32_e32 v78, v0
	v_mov_b32_e32 v79, v0
	v_mov_b32_e32 v88, v0
	v_mov_b32_e32 v89, v0
	v_mov_b32_e32 v90, v0
	v_mov_b32_e32 v91, v0
	v_mov_b32_e32 v92, v0
	v_mov_b32_e32 v93, v0
	v_mov_b32_e32 v94, v0
	v_mov_b32_e32 v95, v0
	v_mov_b32_e32 v104, v0
	v_mov_b32_e32 v105, v0
	v_mov_b32_e32 v106, v0
	v_mov_b32_e32 v107, v0
	v_mov_b32_e32 v108, v0
	v_mov_b32_e32 v109, v0
	v_mov_b32_e32 v110, v0
	v_mov_b32_e32 v111, v0
	v_mov_b32_e32 v120, v0
	v_mov_b32_e32 v121, v0
	v_mov_b32_e32 v122, v0
	v_mov_b32_e32 v123, v0
	v_mov_b32_e32 v124, v0
	v_mov_b32_e32 v125, v0
	v_mov_b32_e32 v126, v0
	v_mov_b32_e32 v127, v0
	.p2alignl 6, 3212836864

; template <class Epi, class Sched, bool ALIGN_EPI = false, bool SP2 = false>
; __device__ __forceinline__ void gemm_phase(PG8_LAS unsigned char* lds, const Gemm g, const Sched& S, const Epi& E, const int tid_arg) {
;     ...
;     for (;;) {
;         const bool has_next = S.next(ui + 1, nxt);
;         const char* nA = has_next ? (const char*)g.A + (size_t)nxt.pm * tstep : cA; const char* nB = has_next ? (const char*)g.Bt + (size_t)nxt.pn * tstep : cB;
;         for (int t = 0; t < nt; t += 2) {
;             const bool last = (t == nt - 2);
;             const char* a1 = cA + (size_t)(t + 1) * kstep;
;             const char* a2 = last ? nA : cA + (size_t)(t + 2) * kstep; const char* b2 = last ? nB : cB + (size_t)(t + 2) * kstep;
;             const char* a3 = a2 + kstep; const char* b3 = b2 + kstep;
;     ...
; #pragma unroll
;         for (int a = 0; a < 2; ++a)
; #pragma unroll
;             for (int b = 0; b < 2; ++b)
; #pragma unroll
;                 for (int m = 0; m < 4; ++m)
; #pragma unroll
;                     for (int n = 0; n < 2; ++n) acc[a][b][m][n] = (f32x4){0.f, 0.f, 0.f, 0.f};
.LBB0_684:
	s_ashr_i32 s37, s36, 31
	s_lshl_b64 s[0:1], s[36:37], 19
	s_add_u32 s38, s2, s0
	s_addc_u32 s39, s3, s1
	s_and_b64 s[0:1], s[12:13], exec
	s_cselect_b32 s17, s39, s5
	s_cselect_b32 s37, s38, s4
	s_ashr_i32 s35, s34, 31
	s_lshl_b64 s[0:1], s[34:35], 19
	s_add_u32 s40, s33, s0
	s_addc_u32 s41, s48, s1
	s_and_b64 s[0:1], s[12:13], exec
	s_cselect_b32 s35, s41, s11
	s_cselect_b32 s46, s40, s10
	s_add_u32 s47, s10, 0x100
	v_mov_b32_e32 v0, 0
	s_addc_u32 s78, s11, 0
	s_mov_b32 s79, -2
	v_mov_b32_e32 v1, v0
	v_mov_b32_e32 v2, v0
	v_mov_b32_e32 v3, v0
	v_mov_b32_e32 v64, v0
	v_mov_b32_e32 v65, v0
	v_mov_b32_e32 v66, v0
	v_mov_b32_e32 v67, v0
	v_mov_b32_e32 v8, v0
	v_mov_b32_e32 v9, v0
	v_mov_b32_e32 v10, v0
	v_mov_b32_e32 v11, v0
	v_mov_b32_e32 v76, v0
	v_mov_b32_e32 v77, v0
	v_mov_b32_e32 v78, v0
	v_mov_b32_e32 v79, v0
	v_mov_b32_e32 v16, v0
	v_mov_b32_e32 v17, v0
	v_mov_b32_e32 v18, v0
	v_mov_b32_e32 v19, v0
	s_waitcnt vmcnt(0)
	v_mov_b64_e32 v[84:85], 0
	v_mov_b64_e32 v[86:87], 0
	v_mov_b64_e32 v[24:25], 0
	v_mov_b64_e32 v[26:27], 0
	v_mov_b64_e32 v[92:93], 0
	v_mov_b64_e32 v[94:95], 0
	v_mov_b64_e32 v[4:5], 0
	v_mov_b64_e32 v[6:7], 0
	v_mov_b64_e32 v[68:69], 0
	v_mov_b64_e32 v[70:71], 0
	v_mov_b64_e32 v[12:13], 0
	v_mov_b64_e32 v[14:15], 0
	v_mov_b64_e32 v[80:81], 0
	v_mov_b64_e32 v[82:83], 0
	v_mov_b64_e32 v[20:21], 0
	v_mov_b64_e32 v[22:23], 0
	v_mov_b64_e32 v[88:89], 0
	v_mov_b64_e32 v[90:91], 0
	v_mov_b64_e32 v[28:29], 0
	v_mov_b64_e32 v[30:31], 0
	v_mov_b64_e32 v[96:97], 0
	v_mov_b64_e32 v[98:99], 0
	v_mov_b64_e32 v[32:33], 0
	v_mov_b64_e32 v[34:35], 0
	v_mov_b64_e32 v[104:105], 0
	v_mov_b64_e32 v[106:107], 0
	v_mov_b64_e32 v[40:41], 0
	v_mov_b64_e32 v[42:43], 0
	v_mov_b64_e32 v[112:113], 0
	v_mov_b64_e32 v[114:115], 0
	v_mov_b64_e32 v[48:49], 0
	v_mov_b64_e32 v[50:51], 0
	v_mov_b64_e32 v[120:121], 0
	v_mov_b64_e32 v[122:123], 0
	v_mov_b64_e32 v[56:57], 0
	v_mov_b64_e32 v[58:59], 0
	v_mov_b64_e32 v[128:129], 0
	v_mov_b64_e32 v[130:131], 0
	v_mov_b64_e32 v[36:37], 0
	v_mov_b64_e32 v[38:39], 0
	v_mov_b64_e32 v[108:109], 0
	v_mov_b64_e32 v[110:111], 0
	v_mov_b64_e32 v[44:45], 0
	v_mov_b64_e32 v[46:47], 0
	v_mov_b64_e32 v[116:117], 0
	v_mov_b64_e32 v[118:119], 0
	v_mov_b64_e32 v[52:53], 0
	v_mov_b64_e32 v[54:55], 0
	v_mov_b64_e32 v[124:125], 0
	v_mov_b64_e32 v[126:127], 0
	v_mov_b64_e32 v[60:61], 0
	v_mov_b64_e32 v[62:63], 0
	v_mov_b64_e32 v[132:133], 0
	v_mov_b64_e32 v[134:135], 0
	.p2alignl 6, 3212836864

; template <class Epi, class Sched, bool ALIGN_EPI = false, bool SP2 = false>
; __device__ __forceinline__ void gemm_phase(PG8_LAS unsigned char* lds, const Gemm g, const Sched& S, const Epi& E, const int tid_arg) {
;     ...
;         for (int t = 0; t < nt; t += 2) {
;             const bool last = (t == nt - 2);
;             const char* a1 = cA + (size_t)(t + 1) * kstep;
;             const char* a2 = last ? nA : cA + (size_t)(t + 2) * kstep; const char* b2 = last ? nB : cB + (size_t)(t + 2) * kstep;
;     ...
; #pragma unroll
;         for (int a = 0; a < 2; ++a)
; #pragma unroll
;             for (int b = 0; b < 2; ++b)
; #pragma unroll
;                 for (int m = 0; m < 4; ++m)
; #pragma unroll
;                     for (int n = 0; n < 2; ++n) acc[a][b][m][n] = (f32x4){0.f, 0.f, 0.f, 0.f};
.LBB0_870:
	s_add_u32 s55, s22, 0x100
	v_mov_b32_e32 v0, 0
	s_addc_u32 s56, s23, 0
	s_mov_b32 s57, -2
	v_mov_b32_e32 v1, v0
	v_mov_b64_e32 v[2:3], 0
	v_mov_b64_e32 v[4:5], 0
	v_mov_b64_e32 v[6:7], 0
	v_mov_b64_e32 v[16:17], 0
	v_mov_b64_e32 v[18:19], 0
	v_mov_b64_e32 v[20:21], 0
	v_mov_b64_e32 v[22:23], 0
	v_mov_b64_e32 v[32:33], 0
	v_mov_b64_e32 v[34:35], 0
	v_mov_b64_e32 v[36:37], 0
	v_mov_b64_e32 v[38:39], 0
	v_mov_b64_e32 v[48:49], 0
	v_mov_b64_e32 v[50:51], 0
	v_mov_b64_e32 v[52:53], 0
	v_mov_b64_e32 v[54:55], 0
	v_mov_b64_e32 v[8:9], 0
	v_mov_b64_e32 v[10:11], 0
	v_mov_b64_e32 v[12:13], 0
	v_mov_b64_e32 v[14:15], 0
	v_mov_b64_e32 v[24:25], 0
	v_mov_b64_e32 v[26:27], 0
	v_mov_b64_e32 v[28:29], 0
	v_mov_b64_e32 v[30:31], 0
	v_mov_b64_e32 v[40:41], 0
	v_mov_b64_e32 v[42:43], 0
	v_mov_b64_e32 v[44:45], 0
	v_mov_b64_e32 v[46:47], 0
	v_mov_b64_e32 v[56:57], 0
	v_mov_b64_e32 v[58:59], 0
	v_mov_b64_e32 v[60:61], 0
	v_mov_b64_e32 v[62:63], 0
	v_mov_b64_e32 v[64:65], 0
	v_mov_b64_e32 v[66:67], 0
	v_mov_b64_e32 v[68:69], 0
	v_mov_b64_e32 v[70:71], 0
	v_mov_b64_e32 v[80:81], 0
	v_mov_b64_e32 v[82:83], 0
	v_mov_b64_e32 v[84:85], 0
	v_mov_b64_e32 v[86:87], 0
	v_mov_b64_e32 v[96:97], 0
	v_mov_b64_e32 v[98:99], 0
	v_mov_b64_e32 v[100:101], 0
	v_mov_b64_e32 v[102:103], 0
	v_mov_b64_e32 v[112:113], 0
	v_mov_b64_e32 v[114:115], 0
	v_mov_b64_e32 v[116:117], 0
	v_mov_b64_e32 v[118:119], 0
	v_mov_b64_e32 v[72:73], 0
	v_mov_b64_e32 v[74:75], 0
	v_mov_b64_e32 v[76:77], 0
	v_mov_b64_e32 v[78:79], 0
	v_mov_b64_e32 v[88:89], 0
	v_mov_b64_e32 v[90:91], 0
	v_mov_b64_e32 v[92:93], 0
	v_mov_b64_e32 v[94:95], 0
	v_mov_b64_e32 v[104:105], 0
	v_mov_b64_e32 v[106:107], 0
	v_mov_b64_e32 v[108:109], 0
	v_mov_b64_e32 v[110:111], 0
	v_mov_b64_e32 v[120:121], 0
	v_mov_b64_e32 v[122:123], 0
	v_mov_b64_e32 v[124:125], 0
	v_mov_b64_e32 v[126:127], 0
	.p2alignl 6, 3212836864

; template <class Epi, class Sched, bool ALIGN_EPI = false, bool SP2 = false>
; __device__ __forceinline__ void gemm_phase(PG8_LAS unsigned char* lds, const Gemm g, const Sched& S, const Epi& E, const int tid_arg) {
;     ...
;     for (;;) {
;         const bool has_next = S.next(ui + 1, nxt);
;         const char* nA = has_next ? (const char*)g.A + (size_t)nxt.pm * tstep : cA; const char* nB = has_next ? (const char*)g.Bt + (size_t)nxt.pn * tstep : cB;
;         for (int t = 0; t < nt; t += 2) {
;             const bool last = (t == nt - 2);
;             const char* a1 = cA + (size_t)(t + 1) * kstep;
;             const char* a2 = last ? nA : cA + (size_t)(t + 2) * kstep; const char* b2 = last ? nB : cB + (size_t)(t + 2) * kstep;
;             const char* a3 = a2 + kstep; const char* b3 = b2 + kstep;
;     ...
; #pragma unroll
;         for (int a = 0; a < 2; ++a)
; #pragma unroll
;             for (int b = 0; b < 2; ++b)
; #pragma unroll
;                 for (int m = 0; m < 4; ++m)
; #pragma unroll
;                     for (int n = 0; n < 2; ++n) acc[a][b][m][n] = (f32x4){0.f, 0.f, 0.f, 0.f};
.LBB0_964:
	s_ashr_i32 s35, s34, 31
	s_lshl_b64 s[0:1], s[34:35], 19
	s_add_u32 s36, s3, s0
	s_addc_u32 s37, s33, s1
	s_and_b64 s[0:1], s[10:11], exec
	s_cselect_b32 s35, s37, s43
	s_cselect_b32 s68, s36, s42
	s_ashr_i32 s31, s30, 31
	s_lshl_b64 s[0:1], s[30:31], 19
	s_add_u32 s38, s44, s0
	s_addc_u32 s39, s45, s1
	s_and_b64 s[0:1], s[10:11], exec
	s_cselect_b32 s31, s39, s41
	s_cselect_b32 s69, s38, s40
	s_add_u32 s70, s40, 0x100
	s_addc_u32 s71, s41, 0
	s_add_u32 s40, s42, 0x40080
	v_mov_b32_e32 v0, 0
	s_addc_u32 s41, s43, 0
	s_mov_b32 s72, -2
	v_mov_b32_e32 v1, v0
	v_mov_b64_e32 v[2:3], 0
	v_mov_b64_e32 v[4:5], 0
	v_mov_b64_e32 v[6:7], 0
	v_mov_b64_e32 v[16:17], 0
	v_mov_b64_e32 v[18:19], 0
	v_mov_b64_e32 v[20:21], 0
	v_mov_b64_e32 v[22:23], 0
	v_mov_b64_e32 v[32:33], 0
	v_mov_b64_e32 v[34:35], 0
	v_mov_b64_e32 v[36:37], 0
	v_mov_b64_e32 v[38:39], 0
	v_mov_b64_e32 v[48:49], 0
	v_mov_b64_e32 v[50:51], 0
	v_mov_b64_e32 v[52:53], 0
	v_mov_b64_e32 v[54:55], 0
	v_mov_b64_e32 v[8:9], 0
	v_mov_b64_e32 v[10:11], 0
	v_mov_b64_e32 v[12:13], 0
	v_mov_b64_e32 v[14:15], 0
	v_mov_b64_e32 v[24:25], 0
	v_mov_b64_e32 v[26:27], 0
	v_mov_b64_e32 v[28:29], 0
	v_mov_b64_e32 v[30:31], 0
	v_mov_b64_e32 v[40:41], 0
	v_mov_b64_e32 v[42:43], 0
	v_mov_b64_e32 v[44:45], 0
	v_mov_b64_e32 v[46:47], 0
	v_mov_b64_e32 v[56:57], 0
	v_mov_b64_e32 v[58:59], 0
	v_mov_b64_e32 v[60:61], 0
	v_mov_b64_e32 v[62:63], 0
	v_mov_b64_e32 v[64:65], 0
	v_mov_b64_e32 v[66:67], 0
	v_mov_b64_e32 v[68:69], 0
	v_mov_b64_e32 v[70:71], 0
	v_mov_b64_e32 v[80:81], 0
	v_mov_b64_e32 v[82:83], 0
	v_mov_b64_e32 v[84:85], 0
	v_mov_b64_e32 v[86:87], 0
	v_mov_b64_e32 v[96:97], 0
	v_mov_b64_e32 v[98:99], 0
	v_mov_b64_e32 v[100:101], 0
	v_mov_b64_e32 v[102:103], 0
	v_mov_b64_e32 v[112:113], 0
	v_mov_b64_e32 v[114:115], 0
	v_mov_b64_e32 v[116:117], 0
	v_mov_b64_e32 v[118:119], 0
	v_mov_b64_e32 v[72:73], 0
	v_mov_b64_e32 v[74:75], 0
	v_mov_b64_e32 v[76:77], 0
	v_mov_b64_e32 v[78:79], 0
	v_mov_b64_e32 v[88:89], 0
	v_mov_b64_e32 v[90:91], 0
	v_mov_b64_e32 v[92:93], 0
	v_mov_b64_e32 v[94:95], 0
	v_mov_b64_e32 v[104:105], 0
	v_mov_b64_e32 v[106:107], 0
	v_mov_b64_e32 v[108:109], 0
	v_mov_b64_e32 v[110:111], 0
	v_mov_b64_e32 v[120:121], 0
	v_mov_b64_e32 v[122:123], 0
	v_mov_b64_e32 v[124:125], 0
	v_mov_b64_e32 v[126:127], 0
	.p2alignl 6, 3212836864

; template <class Epi, class Sched, bool ALIGN_EPI = false, bool SP2 = false>
; __device__ __forceinline__ void gemm_phase(PG8_LAS unsigned char* lds, const Gemm g, const Sched& S, const Epi& E, const int tid_arg) {
;     ...
;     for (;;) {
;         const bool has_next = S.next(ui + 1, nxt);
;         const char* nA = has_next ? (const char*)g.A + (size_t)nxt.pm * tstep : cA; const char* nB = has_next ? (const char*)g.Bt + (size_t)nxt.pn * tstep : cB;
;         for (int t = 0; t < nt; t += 2) {
;             const bool last = (t == nt - 2);
;             const char* a1 = cA + (size_t)(t + 1) * kstep;
;             const char* a2 = last ? nA : cA + (size_t)(t + 2) * kstep; const char* b2 = last ? nB : cB + (size_t)(t + 2) * kstep;
;     ...
; #pragma unroll
;         for (int a = 0; a < 2; ++a)
; #pragma unroll
;             for (int b = 0; b < 2; ++b)
; #pragma unroll
;                 for (int m = 0; m < 4; ++m)
; #pragma unroll
;                     for (int n = 0; n < 2; ++n) acc[a][b][m][n] = (f32x4){0.f, 0.f, 0.f, 0.f};
.LBB0_1044:
	v_mov_b32_e32 v127, 0
	s_and_b64 vcc, exec, s[10:11]
	v_mov_b32_e32 v126, v127
	v_mov_b64_e32 v[124:125], 0
	v_mov_b64_e32 v[122:123], 0
	v_mov_b64_e32 v[120:121], 0
	v_mov_b64_e32 v[110:111], 0
	v_mov_b64_e32 v[108:109], 0
	v_mov_b64_e32 v[106:107], 0
	v_mov_b64_e32 v[104:105], 0
	v_mov_b64_e32 v[94:95], 0
	v_mov_b64_e32 v[92:93], 0
	v_mov_b64_e32 v[90:91], 0
	v_mov_b64_e32 v[88:89], 0
	v_mov_b64_e32 v[78:79], 0
	v_mov_b64_e32 v[76:77], 0
	v_mov_b64_e32 v[74:75], 0
	v_mov_b64_e32 v[72:73], 0
	v_mov_b64_e32 v[118:119], 0
	v_mov_b64_e32 v[116:117], 0
	v_mov_b64_e32 v[114:115], 0
	v_mov_b64_e32 v[112:113], 0
	v_mov_b64_e32 v[102:103], 0
	v_mov_b64_e32 v[100:101], 0
	v_mov_b64_e32 v[98:99], 0
	v_mov_b64_e32 v[96:97], 0
	v_mov_b64_e32 v[86:87], 0
	v_mov_b64_e32 v[84:85], 0
	v_mov_b64_e32 v[82:83], 0
	v_mov_b64_e32 v[80:81], 0
	v_mov_b64_e32 v[70:71], 0
	v_mov_b64_e32 v[68:69], 0
	v_mov_b64_e32 v[66:67], 0
	v_mov_b64_e32 v[64:65], 0
	v_mov_b64_e32 v[62:63], 0
	v_mov_b64_e32 v[60:61], 0
	v_mov_b64_e32 v[58:59], 0
	v_mov_b64_e32 v[56:57], 0
	v_mov_b64_e32 v[46:47], 0
	v_mov_b64_e32 v[44:45], 0
	v_mov_b64_e32 v[42:43], 0
	v_mov_b64_e32 v[40:41], 0
	v_mov_b64_e32 v[30:31], 0
	v_mov_b64_e32 v[28:29], 0
	v_mov_b64_e32 v[26:27], 0
	v_mov_b64_e32 v[24:25], 0
	v_mov_b64_e32 v[14:15], 0
	v_mov_b64_e32 v[12:13], 0
	v_mov_b64_e32 v[10:11], 0
	v_mov_b64_e32 v[8:9], 0
	v_mov_b64_e32 v[54:55], 0
	v_mov_b64_e32 v[52:53], 0
	v_mov_b64_e32 v[50:51], 0
	v_mov_b64_e32 v[48:49], 0
	v_mov_b64_e32 v[38:39], 0
	v_mov_b64_e32 v[36:37], 0
	v_mov_b64_e32 v[34:35], 0
	v_mov_b64_e32 v[32:33], 0
	v_mov_b64_e32 v[22:23], 0
	v_mov_b64_e32 v[20:21], 0
	v_mov_b64_e32 v[18:19], 0
	v_mov_b64_e32 v[16:17], 0
	v_mov_b64_e32 v[6:7], 0
	v_mov_b64_e32 v[4:5], 0
	v_mov_b64_e32 v[2:3], 0
	v_mov_b64_e32 v[0:1], 0
	s_cbranch_vccnz .LBB0_1047
	s_add_u32 s60, s4, 0x100
	s_addc_u32 s61, s5, 0
	s_add_u32 s4, s30, 0x80
	v_mov_b32_e32 v0, 0
	s_addc_u32 s5, s31, 0
	s_mov_b32 s0, 0
	v_mov_b32_e32 v1, v0
	v_mov_b64_e32 v[2:3], 0
	v_mov_b64_e32 v[4:5], 0
	v_mov_b64_e32 v[6:7], 0
	v_mov_b64_e32 v[16:17], 0
	v_mov_b64_e32 v[18:19], 0
	v_mov_b64_e32 v[20:21], 0
	v_mov_b64_e32 v[22:23], 0
	v_mov_b64_e32 v[32:33], 0
	v_mov_b64_e32 v[34:35], 0
	v_mov_b64_e32 v[36:37], 0
	v_mov_b64_e32 v[38:39], 0
	v_mov_b64_e32 v[48:49], 0
	v_mov_b64_e32 v[50:51], 0
	v_mov_b64_e32 v[52:53], 0
	v_mov_b64_e32 v[54:55], 0
	v_mov_b64_e32 v[8:9], 0
	v_mov_b64_e32 v[10:11], 0
	v_mov_b64_e32 v[12:13], 0
	v_mov_b64_e32 v[14:15], 0
	v_mov_b64_e32 v[24:25], 0
	v_mov_b64_e32 v[26:27], 0
	v_mov_b64_e32 v[28:29], 0
	v_mov_b64_e32 v[30:31], 0
	v_mov_b64_e32 v[40:41], 0
	v_mov_b64_e32 v[42:43], 0
	v_mov_b64_e32 v[44:45], 0
	v_mov_b64_e32 v[46:47], 0
	v_mov_b64_e32 v[56:57], 0
	v_mov_b64_e32 v[58:59], 0
	v_mov_b64_e32 v[60:61], 0
	v_mov_b64_e32 v[62:63], 0
	v_mov_b64_e32 v[64:65], 0
	v_mov_b64_e32 v[66:67], 0
	v_mov_b64_e32 v[68:69], 0
	v_mov_b64_e32 v[70:71], 0
	v_mov_b64_e32 v[80:81], 0
	v_mov_b64_e32 v[82:83], 0
	v_mov_b64_e32 v[84:85], 0
	v_mov_b64_e32 v[86:87], 0
	v_mov_b64_e32 v[96:97], 0
	v_mov_b64_e32 v[98:99], 0
	v_mov_b64_e32 v[100:101], 0
	v_mov_b64_e32 v[102:103], 0
	v_mov_b64_e32 v[112:113], 0
	v_mov_b64_e32 v[114:115], 0
	v_mov_b64_e32 v[116:117], 0
	v_mov_b64_e32 v[118:119], 0
	v_mov_b64_e32 v[72:73], 0
	v_mov_b64_e32 v[74:75], 0
	v_mov_b64_e32 v[76:77], 0
	v_mov_b64_e32 v[78:79], 0
	v_mov_b64_e32 v[88:89], 0
	v_mov_b64_e32 v[90:91], 0
	v_mov_b64_e32 v[92:93], 0
	v_mov_b64_e32 v[94:95], 0
	v_mov_b64_e32 v[104:105], 0
	v_mov_b64_e32 v[106:107], 0
	v_mov_b64_e32 v[108:109], 0
	v_mov_b64_e32 v[110:111], 0
	v_mov_b64_e32 v[120:121], 0
	v_mov_b64_e32 v[122:123], 0
	v_mov_b64_e32 v[124:125], 0
	v_mov_b64_e32 v[126:127], 0
	.p2alignl 6, 3212836864

; template <class Epi, class Sched, bool ALIGN_EPI = false, bool SP2 = false>
; __device__ __forceinline__ void gemm_phase(PG8_LAS unsigned char* lds, const Gemm g, const Sched& S, const Epi& E, const int tid_arg) {
;     ...
;     for (;;) {
;         const bool has_next = S.next(ui + 1, nxt);
;         const char* nA = has_next ? (const char*)g.A + (size_t)nxt.pm * tstep : cA; const char* nB = has_next ? (const char*)g.Bt + (size_t)nxt.pn * tstep : cB;
;         for (int t = 0; t < nt; t += 2) {
;             const bool last = (t == nt - 2);
;             const char* a1 = cA + (size_t)(t + 1) * kstep;
;             const char* a2 = last ? nA : cA + (size_t)(t + 2) * kstep; const char* b2 = last ? nB : cB + (size_t)(t + 2) * kstep;
;             const char* a3 = a2 + kstep; const char* b3 = b2 + kstep;
;     ...
; #pragma unroll
;         for (int a = 0; a < 2; ++a)
; #pragma unroll
;             for (int b = 0; b < 2; ++b)
; #pragma unroll
;                 for (int m = 0; m < 4; ++m)
; #pragma unroll
;                     for (int n = 0; n < 2; ++n) acc[a][b][m][n] = (f32x4){0.f, 0.f, 0.f, 0.f};
.LBB0_1178:
	s_ashr_i32 s25, s24, 31
	s_lshl_b64 s[0:1], s[24:25], 19
	s_add_u32 s26, s2, s0
	s_addc_u32 s27, s3, s1
	s_and_b64 s[0:1], s[6:7], exec
	s_cselect_b32 s25, s27, s11
	s_cselect_b32 s36, s26, s10
	s_ashr_i32 s23, s22, 31
	s_lshl_b64 s[0:1], s[22:23], 19
	s_add_u32 s28, s33, s0
	s_addc_u32 s29, s38, s1
	s_and_b64 s[0:1], s[6:7], exec
	s_cselect_b32 s23, s29, s5
	s_cselect_b32 s37, s28, s4
	s_add_u32 s66, s4, 0x100
	s_addc_u32 s67, s5, 0
	s_add_u32 s4, s10, 0x40080
	v_mov_b32_e32 v0, 0
	s_addc_u32 s5, s11, 0
	s_mov_b32 s68, -2
	v_mov_b32_e32 v1, v0
	v_mov_b32_e32 v2, v0
	v_mov_b32_e32 v3, v0
	v_mov_b32_e32 v4, v0
	v_mov_b32_e32 v5, v0
	v_mov_b32_e32 v6, v0
	v_mov_b32_e32 v7, v0
	s_waitcnt vmcnt(0)
	v_mov_b64_e32 v[16:17], 0
	v_mov_b64_e32 v[18:19], 0
	v_mov_b64_e32 v[20:21], 0
	v_mov_b64_e32 v[22:23], 0
	v_mov_b64_e32 v[32:33], 0
	v_mov_b64_e32 v[34:35], 0
	v_mov_b64_e32 v[36:37], 0
	v_mov_b64_e32 v[38:39], 0
	v_mov_b64_e32 v[48:49], 0
	v_mov_b64_e32 v[50:51], 0
	v_mov_b64_e32 v[52:53], 0
	v_mov_b64_e32 v[54:55], 0
	v_mov_b64_e32 v[8:9], 0
	v_mov_b64_e32 v[10:11], 0
	v_mov_b64_e32 v[12:13], 0
	v_mov_b64_e32 v[14:15], 0
	v_mov_b64_e32 v[24:25], 0
	v_mov_b64_e32 v[26:27], 0
	v_mov_b64_e32 v[28:29], 0
	v_mov_b64_e32 v[30:31], 0
	v_mov_b64_e32 v[40:41], 0
	v_mov_b64_e32 v[42:43], 0
	v_mov_b64_e32 v[44:45], 0
	v_mov_b64_e32 v[46:47], 0
	v_mov_b64_e32 v[56:57], 0
	v_mov_b64_e32 v[58:59], 0
	v_mov_b64_e32 v[60:61], 0
	v_mov_b64_e32 v[62:63], 0
	v_mov_b64_e32 v[64:65], 0
	v_mov_b64_e32 v[66:67], 0
	v_mov_b64_e32 v[68:69], 0
	v_mov_b64_e32 v[70:71], 0
	v_mov_b64_e32 v[80:81], 0
	v_mov_b64_e32 v[82:83], 0
	v_mov_b64_e32 v[84:85], 0
	v_mov_b64_e32 v[86:87], 0
	v_mov_b64_e32 v[96:97], 0
	v_mov_b64_e32 v[98:99], 0
	v_mov_b64_e32 v[100:101], 0
	v_mov_b64_e32 v[102:103], 0
	v_mov_b64_e32 v[112:113], 0
	v_mov_b64_e32 v[114:115], 0
	v_mov_b64_e32 v[116:117], 0
	v_mov_b64_e32 v[118:119], 0
	v_mov_b64_e32 v[72:73], 0
	v_mov_b64_e32 v[74:75], 0
	v_mov_b64_e32 v[76:77], 0
	v_mov_b64_e32 v[78:79], 0
	v_mov_b64_e32 v[88:89], 0
	v_mov_b64_e32 v[90:91], 0
	v_mov_b64_e32 v[92:93], 0
	v_mov_b64_e32 v[94:95], 0
	v_mov_b64_e32 v[104:105], 0
	v_mov_b64_e32 v[106:107], 0
	v_mov_b64_e32 v[108:109], 0
	v_mov_b64_e32 v[110:111], 0
	v_mov_b64_e32 v[120:121], 0
	v_mov_b64_e32 v[122:123], 0
	v_mov_b64_e32 v[124:125], 0
	v_mov_b64_e32 v[126:127], 0
	.p2alignl 6, 3212836864

; template <class Epi, class Sched, bool ALIGN_EPI = false, bool SP2 = false>
; __device__ __forceinline__ void gemm_phase(PG8_LAS unsigned char* lds, const Gemm g, const Sched& S, const Epi& E, const int tid_arg) {
;     ...
;     for (;;) {
;         const bool has_next = S.next(ui + 1, nxt);
;         const char* nA = has_next ? (const char*)g.A + (size_t)nxt.pm * tstep : cA; const char* nB = has_next ? (const char*)g.Bt + (size_t)nxt.pn * tstep : cB;
;         for (int t = 0; t < nt; t += 2) {
;             const bool last = (t == nt - 2);
;             const char* a1 = cA + (size_t)(t + 1) * kstep;
;             const char* a2 = last ? nA : cA + (size_t)(t + 2) * kstep; const char* b2 = last ? nB : cB + (size_t)(t + 2) * kstep;
;             const char* a3 = a2 + kstep; const char* b3 = b2 + kstep;
;     ...
; #pragma unroll
;         for (int a = 0; a < 2; ++a)
; #pragma unroll
;             for (int b = 0; b < 2; ++b)
; #pragma unroll
;                 for (int m = 0; m < 4; ++m)
; #pragma unroll
;                     for (int n = 0; n < 2; ++n) acc[a][b][m][n] = (f32x4){0.f, 0.f, 0.f, 0.f};
.LBB0_1458:
	s_ashr_i32 s21, s20, 31
	s_lshl_b64 s[0:1], s[20:21], 19
	s_add_u32 s22, s2, s0
	s_addc_u32 s23, s3, s1
	s_and_b64 s[0:1], s[6:7], exec
	s_cselect_b32 s21, s23, s31
	s_cselect_b32 s27, s22, s30
	s_ashr_i32 s19, s18, 31
	s_lshl_b64 s[0:1], s[18:19], 19
	s_add_u32 s24, s33, s0
	s_addc_u32 s25, s34, s1
	s_and_b64 s[0:1], s[6:7], exec
	s_cselect_b32 s19, s25, s29
	s_cselect_b32 s56, s24, s28
	s_add_u32 s57, s28, 0x100
	s_addc_u32 s58, s29, 0
	s_add_u32 s28, s30, 0x40080
	v_mov_b32_e32 v0, 0
	s_addc_u32 s29, s31, 0
	s_mov_b32 s59, -2
	v_mov_b32_e32 v1, v0
	v_mov_b32_e32 v2, v0
	v_mov_b32_e32 v3, v0
	v_mov_b32_e32 v4, v0
	v_mov_b32_e32 v5, v0
	v_mov_b32_e32 v6, v0
	v_mov_b32_e32 v7, v0
	v_mov_b32_e32 v16, v0
	v_mov_b32_e32 v17, v0
	v_mov_b32_e32 v18, v0
	v_mov_b32_e32 v19, v0
	v_mov_b32_e32 v20, v0
	v_mov_b32_e32 v21, v0
	v_mov_b32_e32 v22, v0
	v_mov_b32_e32 v23, v0
	v_mov_b32_e32 v32, v0
	v_mov_b32_e32 v33, v0
	v_mov_b32_e32 v34, v0
	v_mov_b32_e32 v35, v0
	v_mov_b32_e32 v36, v0
	v_mov_b32_e32 v37, v0
	v_mov_b32_e32 v38, v0
	v_mov_b32_e32 v39, v0
	v_mov_b32_e32 v48, v0
	v_mov_b32_e32 v49, v0
	v_mov_b32_e32 v50, v0
	v_mov_b32_e32 v51, v0
	v_mov_b32_e32 v52, v0
	v_mov_b32_e32 v53, v0
	v_mov_b32_e32 v54, v0
	v_mov_b32_e32 v55, v0
	v_mov_b32_e32 v8, v0
	v_mov_b32_e32 v9, v0
	v_mov_b32_e32 v10, v0
	v_mov_b32_e32 v11, v0
	v_mov_b32_e32 v12, v0
	v_mov_b32_e32 v13, v0
	v_mov_b32_e32 v14, v0
	v_mov_b32_e32 v15, v0
	v_mov_b32_e32 v24, v0
	v_mov_b32_e32 v25, v0
	v_mov_b32_e32 v26, v0
	v_mov_b32_e32 v27, v0
	v_mov_b32_e32 v28, v0
	v_mov_b32_e32 v29, v0
	v_mov_b32_e32 v30, v0
	v_mov_b32_e32 v31, v0
	v_mov_b32_e32 v40, v0
	v_mov_b32_e32 v41, v0
	v_mov_b32_e32 v42, v0
	v_mov_b32_e32 v43, v0
	v_mov_b32_e32 v44, v0
	v_mov_b32_e32 v45, v0
	v_mov_b32_e32 v46, v0
	v_mov_b32_e32 v47, v0
	v_mov_b32_e32 v56, v0
	v_mov_b32_e32 v57, v0
	v_mov_b32_e32 v58, v0
	v_mov_b32_e32 v59, v0
	v_mov_b32_e32 v60, v0
	v_mov_b32_e32 v61, v0
	v_mov_b32_e32 v62, v0
	v_mov_b32_e32 v63, v0
	v_mov_b32_e32 v64, v0
	v_mov_b32_e32 v65, v0
	v_mov_b32_e32 v66, v0
	v_mov_b32_e32 v67, v0
	v_mov_b32_e32 v68, v0
	v_mov_b32_e32 v69, v0
	v_mov_b32_e32 v70, v0
	v_mov_b32_e32 v71, v0
	s_waitcnt vmcnt(0)
	v_mov_b32_e32 v80, v0
	v_mov_b32_e32 v81, v0
	v_mov_b32_e32 v82, v0
	v_mov_b32_e32 v83, v0
	v_mov_b32_e32 v84, v0
	v_mov_b32_e32 v85, v0
	v_mov_b32_e32 v86, v0
	v_mov_b32_e32 v87, v0
	v_mov_b32_e32 v96, v0
	v_mov_b32_e32 v97, v0
	v_mov_b32_e32 v98, v0
	v_mov_b32_e32 v99, v0
	v_mov_b32_e32 v100, v0
	v_mov_b32_e32 v101, v0
	v_mov_b32_e32 v102, v0
	v_mov_b32_e32 v103, v0
	v_mov_b32_e32 v112, v0
	v_mov_b32_e32 v113, v0
	v_mov_b32_e32 v114, v0
	v_mov_b32_e32 v115, v0
	v_mov_b32_e32 v116, v0
	v_mov_b32_e32 v117, v0
	v_mov_b32_e32 v118, v0
	v_mov_b32_e32 v119, v0
	v_mov_b32_e32 v72, v0
	v_mov_b32_e32 v73, v0
	v_mov_b32_e32 v74, v0
	v_mov_b32_e32 v75, v0
	v_mov_b32_e32 v76, v0
	v_mov_b32_e32 v77, v0
	v_mov_b32_e32 v78, v0
	v_mov_b32_e32 v79, v0
	v_mov_b32_e32 v88, v0
	v_mov_b32_e32 v89, v0
	v_mov_b32_e32 v90, v0
	v_mov_b32_e32 v91, v0
	v_mov_b32_e32 v92, v0
	v_mov_b32_e32 v93, v0
	v_mov_b32_e32 v94, v0
	v_mov_b32_e32 v95, v0
	v_mov_b32_e32 v104, v0
	v_mov_b32_e32 v105, v0
	v_mov_b32_e32 v106, v0
	v_mov_b32_e32 v107, v0
	v_mov_b32_e32 v108, v0
	v_mov_b32_e32 v109, v0
	v_mov_b32_e32 v110, v0
	v_mov_b32_e32 v111, v0
	v_mov_b32_e32 v120, v0
	v_mov_b32_e32 v121, v0
	v_mov_b32_e32 v122, v0
	v_mov_b32_e32 v123, v0
	v_mov_b32_e32 v124, v0
	v_mov_b32_e32 v125, v0
	v_mov_b32_e32 v126, v0
	v_mov_b32_e32 v127, v0
	.p2alignl 6, 3212836864

; template <class Epi, class Sched, bool ALIGN_EPI = false, bool SP2 = false>
; __device__ __forceinline__ void gemm_phase(PG8_LAS unsigned char* lds, const Gemm g, const Sched& S, const Epi& E, const int tid_arg) {
;     ...
;     for (;;) {
;         const bool has_next = S.next(ui + 1, nxt);
;         const char* nA = has_next ? (const char*)g.A + (size_t)nxt.pm * tstep : cA; const char* nB = has_next ? (const char*)g.Bt + (size_t)nxt.pn * tstep : cB;
;         for (int t = 0; t < nt; t += 2) {
;             const bool last = (t == nt - 2);
;             const char* a1 = cA + (size_t)(t + 1) * kstep;
;             const char* a2 = last ? nA : cA + (size_t)(t + 2) * kstep; const char* b2 = last ? nB : cB + (size_t)(t + 2) * kstep;
;             const char* a3 = a2 + kstep; const char* b3 = b2 + kstep;
;     ...
; #pragma unroll
;         for (int a = 0; a < 2; ++a)
; #pragma unroll
;             for (int b = 0; b < 2; ++b)
; #pragma unroll
;                 for (int m = 0; m < 4; ++m)
; #pragma unroll
;                     for (int n = 0; n < 2; ++n) acc[a][b][m][n] = (f32x4){0.f, 0.f, 0.f, 0.f};
.LBB0_1546:
	s_ashr_i32 s31, s30, 31
	s_lshl_b64 s[0:1], s[30:31], 19
	s_add_u32 s34, s2, s0
	s_addc_u32 s35, s3, s1
	s_and_b64 s[0:1], s[8:9], exec
	s_cselect_b32 s13, s35, s5
	s_cselect_b32 s31, s34, s4
	s_ashr_i32 s29, s28, 31
	s_lshl_b64 s[0:1], s[28:29], 19
	s_add_u32 s36, s44, s0
	s_addc_u32 s37, s45, s1
	s_and_b64 s[0:1], s[8:9], exec
	s_cselect_b32 s29, s37, s7
	s_cselect_b32 s42, s36, s6
	s_add_u32 s43, s6, 0x100
	v_mov_b32_e32 v0, 0
	s_addc_u32 s75, s7, 0
	s_mov_b32 s78, -2
	v_mov_b32_e32 v1, v0
	v_mov_b32_e32 v2, v0
	v_mov_b32_e32 v3, v0
	v_mov_b32_e32 v64, v0
	v_mov_b32_e32 v65, v0
	v_mov_b32_e32 v66, v0
	v_mov_b32_e32 v67, v0
	v_mov_b32_e32 v8, v0
	v_mov_b32_e32 v9, v0
	v_mov_b32_e32 v10, v0
	v_mov_b32_e32 v11, v0
	v_mov_b32_e32 v76, v0
	v_mov_b32_e32 v77, v0
	v_mov_b32_e32 v78, v0
	v_mov_b32_e32 v79, v0
	v_mov_b32_e32 v16, v0
	v_mov_b32_e32 v17, v0
	v_mov_b32_e32 v18, v0
	v_mov_b32_e32 v19, v0
	s_waitcnt vmcnt(0)
	v_mov_b64_e32 v[84:85], 0
	v_mov_b64_e32 v[86:87], 0
	v_mov_b64_e32 v[24:25], 0
	v_mov_b64_e32 v[26:27], 0
	v_mov_b64_e32 v[92:93], 0
	v_mov_b64_e32 v[94:95], 0
	v_mov_b64_e32 v[4:5], 0
	v_mov_b64_e32 v[6:7], 0
	v_mov_b64_e32 v[68:69], 0
	v_mov_b64_e32 v[70:71], 0
	v_mov_b64_e32 v[12:13], 0
	v_mov_b64_e32 v[14:15], 0
	v_mov_b64_e32 v[80:81], 0
	v_mov_b64_e32 v[82:83], 0
	v_mov_b64_e32 v[20:21], 0
	v_mov_b64_e32 v[22:23], 0
	v_mov_b64_e32 v[88:89], 0
	v_mov_b64_e32 v[90:91], 0
	v_mov_b64_e32 v[28:29], 0
	v_mov_b64_e32 v[30:31], 0
	v_mov_b64_e32 v[96:97], 0
	v_mov_b64_e32 v[98:99], 0
	v_mov_b64_e32 v[32:33], 0
	v_mov_b64_e32 v[34:35], 0
	v_mov_b64_e32 v[104:105], 0
	v_mov_b64_e32 v[106:107], 0
	v_mov_b64_e32 v[40:41], 0
	v_mov_b64_e32 v[42:43], 0
	v_mov_b64_e32 v[112:113], 0
	v_mov_b64_e32 v[114:115], 0
	v_mov_b64_e32 v[48:49], 0
	v_mov_b64_e32 v[50:51], 0
	v_mov_b64_e32 v[120:121], 0
	v_mov_b64_e32 v[122:123], 0
	v_mov_b64_e32 v[56:57], 0
	v_mov_b64_e32 v[58:59], 0
	v_mov_b64_e32 v[128:129], 0
	v_mov_b64_e32 v[130:131], 0
	v_mov_b64_e32 v[36:37], 0
	v_mov_b64_e32 v[38:39], 0
	v_mov_b64_e32 v[108:109], 0
	v_mov_b64_e32 v[110:111], 0
	v_mov_b64_e32 v[44:45], 0
	v_mov_b64_e32 v[46:47], 0
	v_mov_b64_e32 v[116:117], 0
	v_mov_b64_e32 v[118:119], 0
	v_mov_b64_e32 v[52:53], 0
	v_mov_b64_e32 v[54:55], 0
	v_mov_b64_e32 v[124:125], 0
	v_mov_b64_e32 v[126:127], 0
	v_mov_b64_e32 v[60:61], 0
	v_mov_b64_e32 v[62:63], 0
	v_mov_b64_e32 v[132:133], 0
	v_mov_b64_e32 v[134:135], 0
	.p2alignl 6, 3212836864

; template <class Epi, class Sched, bool ALIGN_EPI = false, bool SP2 = false>
; __device__ __forceinline__ void gemm_phase(PG8_LAS unsigned char* lds, const Gemm g, const Sched& S, const Epi& E, const int tid_arg) {
;     ...
;     for (;;) {
;         const bool has_next = S.next(ui + 1, nxt);
;         const char* nA = has_next ? (const char*)g.A + (size_t)nxt.pm * tstep : cA; const char* nB = has_next ? (const char*)g.Bt + (size_t)nxt.pn * tstep : cB;
;         for (int t = 0; t < nt; t += 2) {
;             const bool last = (t == nt - 2);
;             const char* a1 = cA + (size_t)(t + 1) * kstep;
;             const char* a2 = last ? nA : cA + (size_t)(t + 2) * kstep; const char* b2 = last ? nB : cB + (size_t)(t + 2) * kstep;
;             const char* a3 = a2 + kstep; const char* b3 = b2 + kstep;
;     ...
; #pragma unroll
;         for (int a = 0; a < 2; ++a)
; #pragma unroll
;             for (int b = 0; b < 2; ++b)
; #pragma unroll
;                 for (int m = 0; m < 4; ++m)
; #pragma unroll
;                     for (int n = 0; n < 2; ++n) acc[a][b][m][n] = (f32x4){0.f, 0.f, 0.f, 0.f};
.LBB0_1826:
	s_ashr_i32 s39, s38, 31
	s_lshl_b64 s[0:1], s[38:39], 19
	s_add_u32 s40, s3, s0
	s_addc_u32 s41, s33, s1
	s_and_b64 s[0:1], s[6:7], exec
	s_cselect_b32 s39, s41, s47
	s_cselect_b32 s75, s40, s46
	s_ashr_i32 s37, s36, 31
	s_lshl_b64 s[0:1], s[36:37], 19
	s_add_u32 s42, s48, s0
	s_addc_u32 s43, s49, s1
	s_and_b64 s[0:1], s[6:7], exec
	s_cselect_b32 s37, s43, s45
	s_cselect_b32 s78, s42, s44
	s_add_u32 s79, s44, 0x100
	s_addc_u32 s80, s45, 0
	s_add_u32 s44, s46, 0x40080
	v_mov_b32_e32 v0, 0
	s_addc_u32 s45, s47, 0
	s_mov_b32 s81, -2
	v_mov_b32_e32 v1, v0
	v_mov_b64_e32 v[2:3], 0
	v_mov_b64_e32 v[4:5], 0
	v_mov_b64_e32 v[6:7], 0
	v_mov_b64_e32 v[16:17], 0
	v_mov_b64_e32 v[18:19], 0
	v_mov_b64_e32 v[20:21], 0
	v_mov_b64_e32 v[22:23], 0
	v_mov_b64_e32 v[32:33], 0
	v_mov_b64_e32 v[34:35], 0
	v_mov_b64_e32 v[36:37], 0
	v_mov_b64_e32 v[38:39], 0
	v_mov_b64_e32 v[48:49], 0
	v_mov_b64_e32 v[50:51], 0
	v_mov_b64_e32 v[52:53], 0
	v_mov_b64_e32 v[54:55], 0
	v_mov_b64_e32 v[8:9], 0
	v_mov_b64_e32 v[10:11], 0
	v_mov_b64_e32 v[12:13], 0
	v_mov_b64_e32 v[14:15], 0
	v_mov_b64_e32 v[24:25], 0
	v_mov_b64_e32 v[26:27], 0
	v_mov_b64_e32 v[28:29], 0
	v_mov_b64_e32 v[30:31], 0
	v_mov_b64_e32 v[40:41], 0
	v_mov_b64_e32 v[42:43], 0
	v_mov_b64_e32 v[44:45], 0
	v_mov_b64_e32 v[46:47], 0
	v_mov_b64_e32 v[56:57], 0
	v_mov_b64_e32 v[58:59], 0
	v_mov_b64_e32 v[60:61], 0
	v_mov_b64_e32 v[62:63], 0
	v_mov_b64_e32 v[64:65], 0
	v_mov_b64_e32 v[66:67], 0
	v_mov_b64_e32 v[68:69], 0
	v_mov_b64_e32 v[70:71], 0
	v_mov_b64_e32 v[80:81], 0
	v_mov_b64_e32 v[82:83], 0
	v_mov_b64_e32 v[84:85], 0
	v_mov_b64_e32 v[86:87], 0
	v_mov_b64_e32 v[96:97], 0
	v_mov_b64_e32 v[98:99], 0
	v_mov_b64_e32 v[100:101], 0
	v_mov_b64_e32 v[102:103], 0
	v_mov_b64_e32 v[112:113], 0
	v_mov_b64_e32 v[114:115], 0
	v_mov_b64_e32 v[116:117], 0
	v_mov_b64_e32 v[118:119], 0
	v_mov_b64_e32 v[72:73], 0
	v_mov_b64_e32 v[74:75], 0
	v_mov_b64_e32 v[76:77], 0
	v_mov_b64_e32 v[78:79], 0
	v_mov_b64_e32 v[88:89], 0
	v_mov_b64_e32 v[90:91], 0
	v_mov_b64_e32 v[92:93], 0
	v_mov_b64_e32 v[94:95], 0
	v_mov_b64_e32 v[104:105], 0
	v_mov_b64_e32 v[106:107], 0
	v_mov_b64_e32 v[108:109], 0
	v_mov_b64_e32 v[110:111], 0
	v_mov_b64_e32 v[120:121], 0
	v_mov_b64_e32 v[122:123], 0
	v_mov_b64_e32 v[124:125], 0
	v_mov_b64_e32 v[126:127], 0
	.p2alignl 6, 3212836864

; template <class Epi, class Sched, bool ALIGN_EPI = false, bool SP2 = false>
; __device__ __forceinline__ void gemm_phase(PG8_LAS unsigned char* lds, const Gemm g, const Sched& S, const Epi& E, const int tid_arg) {
;     ...
;     for (;;) {
;         const bool has_next = S.next(ui + 1, nxt);
;         const char* nA = has_next ? (const char*)g.A + (size_t)nxt.pm * tstep : cA; const char* nB = has_next ? (const char*)g.Bt + (size_t)nxt.pn * tstep : cB;
;         for (int t = 0; t < nt; t += 2) {
;             const bool last = (t == nt - 2);
;             const char* a1 = cA + (size_t)(t + 1) * kstep;
;             const char* a2 = last ? nA : cA + (size_t)(t + 2) * kstep; const char* b2 = last ? nB : cB + (size_t)(t + 2) * kstep;
;     ...
; #pragma unroll
;         for (int a = 0; a < 2; ++a)
; #pragma unroll
;             for (int b = 0; b < 2; ++b)
; #pragma unroll
;                 for (int m = 0; m < 4; ++m)
; #pragma unroll
;                     for (int n = 0; n < 2; ++n) acc[a][b][m][n] = (f32x4){0.f, 0.f, 0.f, 0.f};
.LBB0_1909:
	v_mov_b32_e32 v127, 0
	s_and_b64 vcc, exec, s[0:1]
	v_mov_b32_e32 v126, v127
	v_mov_b64_e32 v[124:125], 0
	v_mov_b64_e32 v[122:123], 0
	v_mov_b64_e32 v[120:121], 0
	v_mov_b64_e32 v[110:111], 0
	v_mov_b64_e32 v[108:109], 0
	v_mov_b64_e32 v[106:107], 0
	v_mov_b64_e32 v[104:105], 0
	v_mov_b64_e32 v[94:95], 0
	v_mov_b64_e32 v[92:93], 0
	v_mov_b64_e32 v[90:91], 0
	v_mov_b64_e32 v[88:89], 0
	v_mov_b64_e32 v[78:79], 0
	v_mov_b64_e32 v[76:77], 0
	v_mov_b64_e32 v[74:75], 0
	v_mov_b64_e32 v[72:73], 0
	v_mov_b64_e32 v[118:119], 0
	v_mov_b64_e32 v[116:117], 0
	v_mov_b64_e32 v[114:115], 0
	v_mov_b64_e32 v[112:113], 0
	v_mov_b64_e32 v[102:103], 0
	v_mov_b64_e32 v[100:101], 0
	v_mov_b64_e32 v[98:99], 0
	v_mov_b64_e32 v[96:97], 0
	v_mov_b64_e32 v[86:87], 0
	v_mov_b64_e32 v[84:85], 0
	v_mov_b64_e32 v[82:83], 0
	v_mov_b64_e32 v[80:81], 0
	v_mov_b64_e32 v[70:71], 0
	v_mov_b64_e32 v[68:69], 0
	v_mov_b64_e32 v[66:67], 0
	v_mov_b64_e32 v[64:65], 0
	v_mov_b64_e32 v[62:63], 0
	v_mov_b64_e32 v[60:61], 0
	v_mov_b64_e32 v[58:59], 0
	v_mov_b64_e32 v[56:57], 0
	v_mov_b64_e32 v[46:47], 0
	v_mov_b64_e32 v[44:45], 0
	v_mov_b64_e32 v[42:43], 0
	v_mov_b64_e32 v[40:41], 0
	v_mov_b64_e32 v[30:31], 0
	v_mov_b64_e32 v[28:29], 0
	v_mov_b64_e32 v[26:27], 0
	v_mov_b64_e32 v[24:25], 0
	v_mov_b64_e32 v[14:15], 0
	v_mov_b64_e32 v[12:13], 0
	v_mov_b64_e32 v[10:11], 0
	v_mov_b64_e32 v[8:9], 0
	v_mov_b64_e32 v[54:55], 0
	v_mov_b64_e32 v[52:53], 0
	v_mov_b64_e32 v[50:51], 0
	v_mov_b64_e32 v[48:49], 0
	v_mov_b64_e32 v[38:39], 0
	v_mov_b64_e32 v[36:37], 0
	v_mov_b64_e32 v[34:35], 0
	v_mov_b64_e32 v[32:33], 0
	v_mov_b64_e32 v[22:23], 0
	v_mov_b64_e32 v[20:21], 0
	v_mov_b64_e32 v[18:19], 0
	v_mov_b64_e32 v[16:17], 0
	v_mov_b64_e32 v[6:7], 0
	v_mov_b64_e32 v[4:5], 0
	v_mov_b64_e32 v[2:3], 0
	v_mov_b64_e32 v[0:1], 0
	s_cbranch_vccnz .LBB0_1912
	s_add_u32 s63, s34, 0x100
	s_addc_u32 s64, s35, 0
	s_add_u32 s6, s36, 0x80
	v_mov_b32_e32 v0, 0
	s_addc_u32 s7, s37, 0
	s_mov_b32 s34, 0
	v_mov_b32_e32 v1, v0
	v_mov_b64_e32 v[2:3], 0
	v_mov_b64_e32 v[4:5], 0
	v_mov_b64_e32 v[6:7], 0
	v_mov_b64_e32 v[16:17], 0
	v_mov_b64_e32 v[18:19], 0
	v_mov_b64_e32 v[20:21], 0
	v_mov_b64_e32 v[22:23], 0
	v_mov_b64_e32 v[32:33], 0
	v_mov_b64_e32 v[34:35], 0
	v_mov_b64_e32 v[36:37], 0
	v_mov_b64_e32 v[38:39], 0
	v_mov_b64_e32 v[48:49], 0
	v_mov_b64_e32 v[50:51], 0
	v_mov_b64_e32 v[52:53], 0
	v_mov_b64_e32 v[54:55], 0
	v_mov_b64_e32 v[8:9], 0
	v_mov_b64_e32 v[10:11], 0
	v_mov_b64_e32 v[12:13], 0
	v_mov_b64_e32 v[14:15], 0
	v_mov_b64_e32 v[24:25], 0
	v_mov_b64_e32 v[26:27], 0
	v_mov_b64_e32 v[28:29], 0
	v_mov_b64_e32 v[30:31], 0
	v_mov_b64_e32 v[40:41], 0
	v_mov_b64_e32 v[42:43], 0
	v_mov_b64_e32 v[44:45], 0
	v_mov_b64_e32 v[46:47], 0
	v_mov_b64_e32 v[56:57], 0
	v_mov_b64_e32 v[58:59], 0
	v_mov_b64_e32 v[60:61], 0
	v_mov_b64_e32 v[62:63], 0
	v_mov_b64_e32 v[64:65], 0
	v_mov_b64_e32 v[66:67], 0
	v_mov_b64_e32 v[68:69], 0
	v_mov_b64_e32 v[70:71], 0
	v_mov_b64_e32 v[80:81], 0
	v_mov_b64_e32 v[82:83], 0
	v_mov_b64_e32 v[84:85], 0
	v_mov_b64_e32 v[86:87], 0
	v_mov_b64_e32 v[96:97], 0
	v_mov_b64_e32 v[98:99], 0
	v_mov_b64_e32 v[100:101], 0
	v_mov_b64_e32 v[102:103], 0
	v_mov_b64_e32 v[112:113], 0
	v_mov_b64_e32 v[114:115], 0
	v_mov_b64_e32 v[116:117], 0
	v_mov_b64_e32 v[118:119], 0
	v_mov_b64_e32 v[72:73], 0
	v_mov_b64_e32 v[74:75], 0
	v_mov_b64_e32 v[76:77], 0
	v_mov_b64_e32 v[78:79], 0
	v_mov_b64_e32 v[88:89], 0
	v_mov_b64_e32 v[90:91], 0
	v_mov_b64_e32 v[92:93], 0
	v_mov_b64_e32 v[94:95], 0
	v_mov_b64_e32 v[104:105], 0
	v_mov_b64_e32 v[106:107], 0
	v_mov_b64_e32 v[108:109], 0
	v_mov_b64_e32 v[110:111], 0
	v_mov_b64_e32 v[120:121], 0
	v_mov_b64_e32 v[122:123], 0
	v_mov_b64_e32 v[124:125], 0
	v_mov_b64_e32 v[126:127], 0
	.p2alignl 6, 3212836864
